# norm/final/phase0 row sum-of-squares: six ds_bpermute round trips -> DPP row steps + permlane swaps (5 sites), on top of v_dpp_both
# baseline (speedup 1.0000x reference)
.LBB0_371:
	s_or_b64 exec, exec, s[0:1]
	v_mov_b32_e32 v114, v105
	v_mov_b32_e32 v115, v109
	v_mov_b32_e32 v112, v104
	v_mov_b32_e32 v113, v108
	v_pk_mul_f32 v[114:115], v[114:115], v[114:115]
	v_mov_b32_e32 v116, v106
	v_mov_b32_e32 v117, v110
	v_pk_fma_f32 v[112:113], v[112:113], v[112:113], v[114:115]
	v_mov_b32_e32 v118, v107
	v_pk_fma_f32 v[112:113], v[116:117], v[116:117], v[112:113]
	v_mov_b32_e32 v116, v93
	v_mov_b32_e32 v117, v101
	v_mov_b32_e32 v119, v111
	v_mov_b32_e32 v114, v92
	v_mov_b32_e32 v115, v100
	v_pk_mul_f32 v[116:117], v[116:117], v[116:117]
	v_pk_fma_f32 v[112:113], v[118:119], v[118:119], v[112:113]
	v_mov_b32_e32 v118, v94
	v_mov_b32_e32 v119, v102
	v_pk_fma_f32 v[114:115], v[114:115], v[114:115], v[116:117]
	v_mov_b32_e32 v120, v95
	v_mov_b32_e32 v121, v103
	v_pk_fma_f32 v[114:115], v[118:119], v[118:119], v[114:115]
	v_add_f32_e32 v112, v112, v113
	v_pk_fma_f32 v[114:115], v[120:121], v[120:121], v[114:115]
	v_mov_b32_e32 v153, v139
	v_add_f32_e32 v112, v115, v112
	v_add_f32_e32 v112, v114, v112
	v_mov_b32_e32 v155, v139
	v_mov_b32_e32 v157, v139
	v_lshl_add_u64 v[168:169], s[8:9], 0, v[168:169]
	v_cndmask_b32_e32 v169, v163, v169, vcc
	v_cndmask_b32_e32 v168, v162, v168, vcc
	s_nop 1
	v_add_f32_dpp v112, v112, v112 quad_perm:[1,0,3,2] row_mask:0xf bank_mask:0xf bound_ctrl:1
	s_nop 1
	v_add_f32_dpp v112, v112, v112 quad_perm:[2,3,0,1] row_mask:0xf bank_mask:0xf bound_ctrl:1
	s_nop 1
	v_add_f32_dpp v112, v112, v112 row_ror:4 row_mask:0xf bank_mask:0xf bound_ctrl:1
	s_nop 1
	v_add_f32_dpp v112, v112, v112 row_ror:8 row_mask:0xf bank_mask:0xf bound_ctrl:1
	s_nop 1
	v_mov_b32_e32 v113, v112
	s_nop 1
	v_permlane16_swap_b32_e32 v113, v112
	v_add_f32_e32 v112, v112, v113
	v_mov_b32_e32 v113, v112
	s_nop 1
	v_permlane32_swap_b32_e32 v113, v112
	v_add_f32_e32 v112, v112, v113
	s_waitcnt lgkmcnt(0)
	v_fmamk_f32 v112, v112, 0x3a800000, v183
	v_cmp_gt_f32_e64 s[0:1], s18, v112
	v_mul_f32_e32 v113, 0x4b800000, v112
	s_nop 0
	v_cndmask_b32_e64 v112, v112, v113, s[0:1]
	v_rsq_f32_e32 v112, v112
	s_nop 0
	v_mul_f32_e32 v113, 0x45800000, v112
	v_cndmask_b32_e64 v164, v112, v113, s[0:1]
	v_cmp_gt_i32_e64 s[0:1], s35, v166
	v_add_u32_e32 v112, 0xffffc004, v166
	v_pk_mul_f32 v[108:109], v[108:109], v[164:165] op_sel_hi:[1,0]
	v_cndmask_b32_e64 v114, v112, v160, s[0:1]
	v_mov_b64_e32 v[112:113], s[76:77]
	v_mad_i64_i32 v[112:113], s[0:1], v114, s19, v[112:113]
	v_lshl_add_u64 v[170:171], v[112:113], 0, s[12:13]
	v_lshl_add_u64 v[172:173], v[112:113], 0, v[138:139]
	v_lshl_add_u64 v[116:117], v[170:171], 0, v[138:139]
	global_load_dwordx4 v[112:115], v[172:173], off
	v_pk_mul_f32 v[108:109], v[0:1], v[108:109]
	global_load_dwordx4 v[116:119], v[116:117], off
	v_pk_mul_f32 v[110:111], v[110:111], v[164:165] op_sel_hi:[1,0]
	global_load_dwordx4 v[128:131], v[172:173], off offset:1024
	v_pk_mul_f32 v[110:111], v[2:3], v[110:111]
	s_waitcnt vmcnt(1)
	v_pk_add_f32 v[116:117], v[116:117], 1.0 op_sel_hi:[1,0]
	s_nop 0
	v_pk_fma_f32 v[108:109], v[116:117], v[108:109], v[112:113]
	v_lshl_add_u64 v[112:113], v[170:171], 0, v[152:153]
	v_pk_add_f32 v[118:119], v[118:119], 1.0 op_sel_hi:[1,0]
	global_load_dwordx4 v[132:135], v[112:113], off
	global_load_dwordx4 v[120:123], v[172:173], off offset:2048
	v_lshl_add_u64 v[112:113], v[170:171], 0, v[154:155]
	v_lshl_add_u64 v[116:117], v[170:171], 0, v[156:157]
	v_pk_fma_f32 v[110:111], v[118:119], v[110:111], v[114:115]
	global_load_dwordx4 v[124:127], v[112:113], off
	s_nop 0
	global_load_dwordx4 v[112:115], v[172:173], off offset:3072
	v_and_b32_e32 v153, 0xfff, v166
	global_load_dwordx4 v[116:119], v[116:117], off
	v_cmp_eq_u32_e64 s[0:1], s38, v153
	s_or_b64 s[0:1], vcc, s[0:1]
	v_mad_i64_i32 v[170:171], s[16:17], v166, s39, v[144:145]
	v_cvt_pk_bf16_f32 v172, v108, v109
	v_cvt_pk_bf16_f32 v173, v110, v111
	global_store_dwordx2 v[170:171], v[172:173], off
	s_and_saveexec_b64 s[16:17], s[0:1]
	s_cbranch_execz .LBB0_373
	v_lshl_add_u64 v[172:173], v[168:169], 0, v[138:139]
	global_store_dwordx4 v[172:173], v[108:111], off

.LBB0_1522:
	s_or_b64 exec, exec, s[16:17]
	v_ashrrev_i32_e32 v63, 12, v54
	v_add_u32_e32 v64, 0xffffc004, v54
	v_cmp_gt_i32_e64 s[0:1], s19, v54
	v_mov_b32_e32 v82, v29
	v_mov_b32_e32 v83, v25
	v_cndmask_b32_e64 v54, v64, v63, s[0:1]
	v_mov_b64_e32 v[64:65], s[76:77]
	v_mad_i64_i32 v[64:65], s[0:1], v54, s20, v[64:65]
	v_lshl_add_u64 v[64:65], v[64:65], 0, v[48:49]
	v_mov_b32_e32 v80, v28
	v_mov_b32_e32 v81, v24
	v_pk_mul_f32 v[82:83], v[82:83], v[82:83]
	v_add_co_u32_e64 v68, s[0:1], s19, v64
	v_pk_fma_f32 v[80:81], v[80:81], v[80:81], v[82:83]
	v_mov_b32_e32 v82, v30
	v_mov_b32_e32 v83, v26
	v_addc_co_u32_e64 v69, s[0:1], 0, v65, s[0:1]
	v_pk_fma_f32 v[80:81], v[82:83], v[82:83], v[80:81]
	v_mov_b32_e32 v82, v31
	v_mov_b32_e32 v83, v27
	v_mov_b32_e32 v84, v21
	v_mov_b32_e32 v85, v17
	v_lshl_add_u64 v[92:93], v[64:65], 0, s[12:13]
	v_lshl_add_u64 v[88:89], v[64:65], 0, s[14:15]
	global_load_dwordx4 v[64:67], v[68:69], off offset:-4096
	s_nop 0
	global_load_dwordx4 v[68:71], v[68:69], off
	s_nop 0
	global_load_dwordx4 v[72:75], v[92:93], off offset:1024
	global_load_dwordx4 v[76:79], v[88:89], off offset:1024
	v_pk_fma_f32 v[80:81], v[82:83], v[82:83], v[80:81]
	v_mov_b32_e32 v82, v20
	v_mov_b32_e32 v83, v16
	v_pk_mul_f32 v[84:85], v[84:85], v[84:85]
	v_add_f32_e32 v54, v80, v81
	v_pk_fma_f32 v[82:83], v[82:83], v[82:83], v[84:85]
	v_mov_b32_e32 v84, v22
	v_mov_b32_e32 v85, v18
	v_pk_fma_f32 v[82:83], v[84:85], v[84:85], v[82:83]
	v_mov_b32_e32 v84, v23
	v_mov_b32_e32 v85, v19
	v_pk_fma_f32 v[82:83], v[84:85], v[84:85], v[82:83]
	global_load_dwordx4 v[84:87], v[92:93], off offset:2048
	v_add_f32_e32 v54, v54, v82
	v_add_f32_e32 v54, v54, v83
	global_load_dwordx4 v[80:83], v[88:89], off offset:2048
	s_nop 0
	global_load_dwordx4 v[88:91], v[88:89], off offset:3072
	s_nop 0
	global_load_dwordx4 v[92:95], v[92:93], off offset:3072
	s_and_b64 s[16:17], exec, vcc
	s_or_b64 s[10:11], s[16:17], s[10:11]
	v_lshl_add_u64 v[52:53], v[52:53], 0, s[8:9]
	s_nop 1
	v_add_f32_dpp v54, v54, v54 quad_perm:[1,0,3,2] row_mask:0xf bank_mask:0xf bound_ctrl:1
	s_nop 1
	v_add_f32_dpp v54, v54, v54 quad_perm:[2,3,0,1] row_mask:0xf bank_mask:0xf bound_ctrl:1
	s_nop 1
	v_add_f32_dpp v54, v54, v54 row_ror:4 row_mask:0xf bank_mask:0xf bound_ctrl:1
	s_nop 1
	v_add_f32_dpp v54, v54, v54 row_ror:8 row_mask:0xf bank_mask:0xf bound_ctrl:1
	s_nop 1
	v_mov_b32_e32 v63, v54
	s_nop 1
	v_permlane16_swap_b32_e32 v63, v54
	v_add_f32_e32 v54, v54, v63
	v_mov_b32_e32 v63, v54
	s_nop 1
	v_permlane32_swap_b32_e32 v63, v54
	v_add_f32_e32 v54, v54, v63
	s_waitcnt lgkmcnt(0)
	v_fmamk_f32 v54, v54, 0x3a800000, v61
	v_mul_f32_e32 v63, 0x4b800000, v54
	v_cmp_gt_f32_e64 s[0:1], s21, v54
	s_nop 1
	v_cndmask_b32_e64 v54, v54, v63, s[0:1]
	v_rsq_f32_e32 v54, v54
	s_nop 0
	v_mul_f32_e32 v63, 0x45800000, v54
	v_cndmask_b32_e64 v54, v54, v63, s[0:1]
	v_mul_f32_e32 v28, v28, v54
	v_mul_f32_e32 v29, v29, v54
	v_mul_f32_e32 v28, v0, v28
	v_mul_f32_e32 v30, v30, v54
	v_mul_f32_e32 v31, v31, v54
	v_mul_f32_e32 v29, v1, v29
	v_mul_f32_e32 v30, v2, v30
	v_mul_f32_e32 v31, v3, v31
	v_mul_f32_e32 v24, v24, v54
	v_mul_f32_e32 v24, v4, v24
	v_mul_f32_e32 v25, v25, v54
	v_mul_f32_e32 v25, v5, v25
	s_waitcnt vmcnt(6)
	v_add_f32_e32 v63, 1.0, v68
	v_add_f32_e32 v68, 1.0, v69
	v_fma_f32 v28, v63, v28, v64
	v_add_f32_e32 v69, 1.0, v70
	v_add_f32_e32 v70, 1.0, v71
	v_fma_f32 v29, v68, v29, v65
	v_cvt_pk_bf16_f32 v28, v28, v29
	v_fma_f32 v30, v69, v30, v66
	v_fmac_f32_e32 v67, v70, v31
	v_cvt_pk_bf16_f32 v29, v30, v67
	global_store_dwordx2 v[50:51], v[28:29], off
	s_waitcnt vmcnt(5)
	v_add_f32_e32 v28, 1.0, v76
	v_fma_f32 v24, v28, v24, v72
	v_add_f32_e32 v28, 1.0, v77
	v_mul_f32_e32 v26, v26, v54
	v_fma_f32 v25, v28, v25, v73
	v_mul_f32_e32 v26, v6, v26
	v_add_f32_e32 v28, 1.0, v78
	v_mul_f32_e32 v27, v27, v54
	v_fma_f32 v26, v28, v26, v74
	v_mul_f32_e32 v27, v7, v27
	v_add_f32_e32 v28, 1.0, v79
	v_cvt_pk_bf16_f32 v24, v24, v25
	v_mul_f32_e32 v20, v20, v54
	v_fmac_f32_e32 v75, v28, v27
	v_cvt_pk_bf16_f32 v25, v26, v75
	global_store_dwordx2 v[50:51], v[24:25], off offset:512
	v_mul_f32_e32 v20, v8, v20
	s_waitcnt vmcnt(4)
	v_add_f32_e32 v24, 1.0, v80
	v_mul_f32_e32 v21, v21, v54
	v_fma_f32 v20, v24, v20, v84
	v_mul_f32_e32 v21, v9, v21
	v_add_f32_e32 v24, 1.0, v81
	v_mul_f32_e32 v22, v22, v54
	v_fma_f32 v21, v24, v21, v85
	v_mul_f32_e32 v22, v10, v22
	v_add_f32_e32 v24, 1.0, v82
	v_mul_f32_e32 v23, v23, v54
	v_fma_f32 v22, v24, v22, v86
	v_mul_f32_e32 v23, v11, v23
	v_add_f32_e32 v24, 1.0, v83
	v_cvt_pk_bf16_f32 v20, v20, v21
	v_mul_f32_e32 v16, v16, v54
	v_fmac_f32_e32 v87, v24, v23
	v_cvt_pk_bf16_f32 v21, v22, v87
	global_store_dwordx2 v[50:51], v[20:21], off offset:1024
	v_mul_f32_e32 v16, v12, v16
	s_waitcnt vmcnt(4)
	v_add_f32_e32 v20, 1.0, v88
	v_mul_f32_e32 v17, v17, v54
	s_waitcnt vmcnt(3)
	v_fma_f32 v16, v20, v16, v92
	v_mul_f32_e32 v17, v13, v17
	v_add_f32_e32 v20, 1.0, v89
	v_mul_f32_e32 v18, v18, v54
	v_fma_f32 v17, v20, v17, v93
	v_mul_f32_e32 v18, v14, v18
	v_add_f32_e32 v20, 1.0, v90
	v_mul_f32_e32 v19, v19, v54
	v_fma_f32 v18, v20, v18, v94
	v_mul_f32_e32 v19, v15, v19
	v_add_f32_e32 v20, 1.0, v91
	v_fmac_f32_e32 v95, v20, v19
	v_cvt_pk_bf16_f32 v16, v16, v17
	v_cvt_pk_bf16_f32 v17, v18, v95
	global_store_dwordx2 v[50:51], v[16:17], off offset:1536
	v_lshl_add_u64 v[50:51], v[50:51], 0, s[54:55]
	v_mov_b32_e32 v54, v62
	v_mov_b64_e32 v[28:29], v[32:33]
	v_mov_b64_e32 v[30:31], v[34:35]
	v_mov_b64_e32 v[24:25], v[36:37]
	v_mov_b64_e32 v[26:27], v[38:39]
	v_mov_b64_e32 v[20:21], v[40:41]
	v_mov_b64_e32 v[22:23], v[42:43]
	v_mov_b64_e32 v[16:17], v[44:45]
	v_mov_b64_e32 v[18:19], v[46:47]
	s_andn2_b64 exec, exec, s[10:11]
	s_cbranch_execz .LBB0_1525

.LBB0_1855:
	s_or_b64 exec, exec, s[12:13]
	v_ashrrev_i32_e32 v63, 12, v54
	v_add_u32_e32 v64, 0xffffc004, v54
	v_cmp_gt_i32_e64 s[0:1], s16, v54
	v_mov_b32_e32 v82, v29
	v_mov_b32_e32 v83, v25
	v_cndmask_b32_e64 v54, v64, v63, s[0:1]
	v_add_u32_e32 v54, 0x84, v54
	v_mov_b64_e32 v[64:65], s[76:77]
	v_mad_i64_i32 v[64:65], s[0:1], v54, s17, v[64:65]
	v_mov_b32_e32 v80, v28
	v_mov_b32_e32 v81, v24
	v_pk_mul_f32 v[82:83], v[82:83], v[82:83]
	v_lshl_add_u64 v[92:93], v[64:65], 0, v[48:49]
	v_pk_fma_f32 v[80:81], v[80:81], v[80:81], v[82:83]
	v_mov_b32_e32 v82, v30
	v_mov_b32_e32 v83, v26
	v_add_co_u32_e64 v64, s[0:1], s14, v92
	v_pk_fma_f32 v[80:81], v[82:83], v[82:83], v[80:81]
	v_mov_b32_e32 v82, v31
	v_mov_b32_e32 v83, v27
	v_mov_b32_e32 v84, v21
	v_mov_b32_e32 v85, v17
	v_addc_co_u32_e64 v65, s[0:1], 0, v93, s[0:1]
	v_pk_fma_f32 v[80:81], v[82:83], v[82:83], v[80:81]
	v_mov_b32_e32 v82, v20
	v_mov_b32_e32 v83, v16
	v_pk_mul_f32 v[84:85], v[84:85], v[84:85]
	v_lshl_add_u64 v[88:89], v[92:93], 0, s[6:7]
	global_load_dwordx4 v[64:67], v[64:65], off
	s_nop 0
	global_load_dwordx4 v[68:71], v[92:93], off
	global_load_dwordx4 v[72:75], v[92:93], off offset:1024
	global_load_dwordx4 v[76:79], v[88:89], off offset:1024
	v_pk_fma_f32 v[82:83], v[82:83], v[82:83], v[84:85]
	v_mov_b32_e32 v84, v22
	v_mov_b32_e32 v85, v18
	v_pk_fma_f32 v[82:83], v[84:85], v[84:85], v[82:83]
	v_mov_b32_e32 v84, v23
	v_mov_b32_e32 v85, v19
	v_pk_fma_f32 v[82:83], v[84:85], v[84:85], v[82:83]
	v_add_f32_e32 v54, v80, v81
	v_add_f32_e32 v54, v54, v82
	v_add_f32_e32 v54, v54, v83
	global_load_dwordx4 v[80:83], v[88:89], off offset:2048
	global_load_dwordx4 v[84:87], v[92:93], off offset:2048
	s_nop 0
	global_load_dwordx4 v[88:91], v[88:89], off offset:3072
	s_nop 0
	global_load_dwordx4 v[92:95], v[92:93], off offset:3072
	s_and_b64 s[12:13], exec, vcc
	s_or_b64 s[10:11], s[12:13], s[10:11]
	v_lshl_add_u64 v[52:53], v[52:53], 0, s[8:9]
	s_nop 1
	v_add_f32_dpp v54, v54, v54 quad_perm:[1,0,3,2] row_mask:0xf bank_mask:0xf bound_ctrl:1
	s_nop 1
	v_add_f32_dpp v54, v54, v54 quad_perm:[2,3,0,1] row_mask:0xf bank_mask:0xf bound_ctrl:1
	s_nop 1
	v_add_f32_dpp v54, v54, v54 row_ror:4 row_mask:0xf bank_mask:0xf bound_ctrl:1
	s_nop 1
	v_add_f32_dpp v54, v54, v54 row_ror:8 row_mask:0xf bank_mask:0xf bound_ctrl:1
	s_nop 1
	v_mov_b32_e32 v63, v54
	s_nop 1
	v_permlane16_swap_b32_e32 v63, v54
	v_add_f32_e32 v54, v54, v63
	v_mov_b32_e32 v63, v54
	s_nop 1
	v_permlane32_swap_b32_e32 v63, v54
	v_add_f32_e32 v54, v54, v63
	s_waitcnt lgkmcnt(0)
	v_fmamk_f32 v54, v54, 0x3a800000, v61
	v_mul_f32_e32 v63, 0x4b800000, v54
	v_cmp_gt_f32_e64 s[0:1], s18, v54
	s_nop 1
	v_cndmask_b32_e64 v54, v54, v63, s[0:1]
	v_rsq_f32_e32 v54, v54
	s_nop 0
	v_mul_f32_e32 v63, 0x45800000, v54
	v_cndmask_b32_e64 v54, v54, v63, s[0:1]
	v_mul_f32_e32 v28, v28, v54
	v_mul_f32_e32 v29, v29, v54
	v_mul_f32_e32 v28, v8, v28
	v_mul_f32_e32 v30, v30, v54
	v_mul_f32_e32 v31, v31, v54
	v_mul_f32_e32 v29, v9, v29
	v_mul_f32_e32 v24, v24, v54
	v_mul_f32_e32 v30, v10, v30
	v_mul_f32_e32 v31, v11, v31
	v_mul_f32_e32 v24, v0, v24
	v_mul_f32_e32 v25, v25, v54
	v_mul_f32_e32 v25, v1, v25
	v_mul_f32_e32 v26, v26, v54
	v_mul_f32_e32 v26, v2, v26
	v_mul_f32_e32 v27, v27, v54
	s_waitcnt vmcnt(7)
	v_add_f32_e32 v63, 1.0, v64
	v_add_f32_e32 v64, 1.0, v65
	s_waitcnt vmcnt(6)
	v_fma_f32 v28, v63, v28, v68
	v_add_f32_e32 v65, 1.0, v66
	v_add_f32_e32 v66, 1.0, v67
	v_fma_f32 v29, v64, v29, v69
	v_cvt_pk_bf16_f32 v28, v28, v29
	v_fma_f32 v30, v65, v30, v70
	v_fmac_f32_e32 v71, v66, v31
	v_cvt_pk_bf16_f32 v29, v30, v71
	global_store_dwordx2 v[50:51], v[28:29], off
	s_waitcnt vmcnt(5)
	v_add_f32_e32 v28, 1.0, v76
	v_fma_f32 v24, v28, v24, v72
	v_add_f32_e32 v28, 1.0, v77
	v_fma_f32 v25, v28, v25, v73
	v_add_f32_e32 v28, 1.0, v78
	v_fma_f32 v26, v28, v26, v74
	v_mul_f32_e32 v27, v3, v27
	v_add_f32_e32 v28, 1.0, v79
	v_cvt_pk_bf16_f32 v24, v24, v25
	v_mul_f32_e32 v20, v20, v54
	v_fmac_f32_e32 v75, v28, v27
	v_cvt_pk_bf16_f32 v25, v26, v75
	global_store_dwordx2 v[50:51], v[24:25], off offset:512
	v_mul_f32_e32 v20, v4, v20
	s_waitcnt vmcnt(5)
	v_add_f32_e32 v24, 1.0, v80
	v_mul_f32_e32 v21, v21, v54
	s_waitcnt vmcnt(4)
	v_fma_f32 v20, v24, v20, v84
	v_mul_f32_e32 v21, v5, v21
	v_add_f32_e32 v24, 1.0, v81
	v_mul_f32_e32 v22, v22, v54
	v_fma_f32 v21, v24, v21, v85
	v_mul_f32_e32 v22, v6, v22
	v_add_f32_e32 v24, 1.0, v82
	v_mul_f32_e32 v23, v23, v54
	v_fma_f32 v22, v24, v22, v86
	v_mul_f32_e32 v23, v7, v23
	v_add_f32_e32 v24, 1.0, v83
	v_cvt_pk_bf16_f32 v20, v20, v21
	v_mul_f32_e32 v16, v16, v54
	v_fmac_f32_e32 v87, v24, v23
	v_cvt_pk_bf16_f32 v21, v22, v87
	global_store_dwordx2 v[50:51], v[20:21], off offset:1024
	v_mul_f32_e32 v16, v12, v16
	s_waitcnt vmcnt(4)
	v_add_f32_e32 v20, 1.0, v88
	v_mul_f32_e32 v17, v17, v54
	s_waitcnt vmcnt(3)
	v_fma_f32 v16, v20, v16, v92
	v_mul_f32_e32 v17, v13, v17
	v_add_f32_e32 v20, 1.0, v89
	v_mul_f32_e32 v18, v18, v54
	v_fma_f32 v17, v20, v17, v93
	v_mul_f32_e32 v18, v14, v18
	v_add_f32_e32 v20, 1.0, v90
	v_mul_f32_e32 v19, v19, v54
	v_fma_f32 v18, v20, v18, v94
	v_mul_f32_e32 v19, v15, v19
	v_add_f32_e32 v20, 1.0, v91
	v_fmac_f32_e32 v95, v20, v19
	v_cvt_pk_bf16_f32 v16, v16, v17
	v_cvt_pk_bf16_f32 v17, v18, v95
	global_store_dwordx2 v[50:51], v[16:17], off offset:1536
	v_lshl_add_u64 v[50:51], v[50:51], 0, s[54:55]
	v_mov_b32_e32 v54, v62
	v_mov_b64_e32 v[28:29], v[32:33]
	v_mov_b64_e32 v[30:31], v[34:35]
	v_mov_b64_e32 v[24:25], v[36:37]
	v_mov_b64_e32 v[26:27], v[38:39]
	v_mov_b64_e32 v[20:21], v[40:41]
	v_mov_b64_e32 v[22:23], v[42:43]
	v_mov_b64_e32 v[16:17], v[44:45]
	v_mov_b64_e32 v[18:19], v[46:47]
	s_andn2_b64 exec, exec, s[10:11]
	s_cbranch_execz .LBB0_1858

.LBB0_2947:
	s_or_b64 exec, exec, s[14:15]
	v_ashrrev_i32_e32 v63, 12, v54
	v_add_u32_e32 v64, 0xffffc004, v54
	v_cmp_gt_i32_e64 s[0:1], s17, v54
	v_mov_b32_e32 v82, v29
	v_mov_b32_e32 v83, v25
	v_cndmask_b32_e64 v54, v64, v63, s[0:1]
	v_add_u32_e32 v54, 0x84, v54
	v_mov_b64_e32 v[64:65], s[76:77]
	v_mad_i64_i32 v[64:65], s[0:1], v54, s18, v[64:65]
	v_lshl_add_u64 v[64:65], v[64:65], 0, v[48:49]
	v_mov_b32_e32 v80, v28
	v_mov_b32_e32 v81, v24
	v_pk_mul_f32 v[82:83], v[82:83], v[82:83]
	v_add_co_u32_e64 v68, s[0:1], s17, v64
	v_pk_fma_f32 v[80:81], v[80:81], v[80:81], v[82:83]
	v_mov_b32_e32 v82, v30
	v_mov_b32_e32 v83, v26
	v_addc_co_u32_e64 v69, s[0:1], 0, v65, s[0:1]
	v_pk_fma_f32 v[80:81], v[82:83], v[82:83], v[80:81]
	v_mov_b32_e32 v82, v31
	v_mov_b32_e32 v83, v27
	v_mov_b32_e32 v84, v21
	v_mov_b32_e32 v85, v17
	v_lshl_add_u64 v[92:93], v[64:65], 0, s[10:11]
	v_lshl_add_u64 v[88:89], v[64:65], 0, s[12:13]
	global_load_dwordx4 v[64:67], v[68:69], off offset:-4096
	s_nop 0
	global_load_dwordx4 v[68:71], v[68:69], off
	s_nop 0
	global_load_dwordx4 v[72:75], v[92:93], off offset:1024
	global_load_dwordx4 v[76:79], v[88:89], off offset:1024
	v_pk_fma_f32 v[80:81], v[82:83], v[82:83], v[80:81]
	v_mov_b32_e32 v82, v20
	v_mov_b32_e32 v83, v16
	v_pk_mul_f32 v[84:85], v[84:85], v[84:85]
	v_add_f32_e32 v54, v80, v81
	v_pk_fma_f32 v[82:83], v[82:83], v[82:83], v[84:85]
	v_mov_b32_e32 v84, v22
	v_mov_b32_e32 v85, v18
	v_pk_fma_f32 v[82:83], v[84:85], v[84:85], v[82:83]
	v_mov_b32_e32 v84, v23
	v_mov_b32_e32 v85, v19
	v_pk_fma_f32 v[82:83], v[84:85], v[84:85], v[82:83]
	global_load_dwordx4 v[84:87], v[92:93], off offset:2048
	v_add_f32_e32 v54, v54, v82
	v_add_f32_e32 v54, v54, v83
	global_load_dwordx4 v[80:83], v[88:89], off offset:2048
	s_nop 0
	global_load_dwordx4 v[88:91], v[88:89], off offset:3072
	s_nop 0
	global_load_dwordx4 v[92:95], v[92:93], off offset:3072
	s_and_b64 s[14:15], exec, vcc
	s_or_b64 s[8:9], s[14:15], s[8:9]
	v_lshl_add_u64 v[52:53], v[52:53], 0, s[6:7]
	s_nop 1
	v_add_f32_dpp v54, v54, v54 quad_perm:[1,0,3,2] row_mask:0xf bank_mask:0xf bound_ctrl:1
	s_nop 1
	v_add_f32_dpp v54, v54, v54 quad_perm:[2,3,0,1] row_mask:0xf bank_mask:0xf bound_ctrl:1
	s_nop 1
	v_add_f32_dpp v54, v54, v54 row_ror:4 row_mask:0xf bank_mask:0xf bound_ctrl:1
	s_nop 1
	v_add_f32_dpp v54, v54, v54 row_ror:8 row_mask:0xf bank_mask:0xf bound_ctrl:1
	s_nop 1
	v_mov_b32_e32 v63, v54
	s_nop 1
	v_permlane16_swap_b32_e32 v63, v54
	v_add_f32_e32 v54, v54, v63
	v_mov_b32_e32 v63, v54
	s_nop 1
	v_permlane32_swap_b32_e32 v63, v54
	v_add_f32_e32 v54, v54, v63
	s_waitcnt lgkmcnt(0)
	v_fmamk_f32 v54, v54, 0x3a800000, v61
	v_mul_f32_e32 v63, 0x4b800000, v54
	v_cmp_gt_f32_e64 s[0:1], s19, v54
	s_nop 1
	v_cndmask_b32_e64 v54, v54, v63, s[0:1]
	v_rsq_f32_e32 v54, v54
	s_nop 0
	v_mul_f32_e32 v63, 0x45800000, v54
	v_cndmask_b32_e64 v54, v54, v63, s[0:1]
	v_mul_f32_e32 v28, v28, v54
	v_mul_f32_e32 v29, v29, v54
	v_mul_f32_e32 v28, v8, v28
	v_mul_f32_e32 v30, v30, v54
	v_mul_f32_e32 v31, v31, v54
	v_mul_f32_e32 v29, v9, v29
	v_mul_f32_e32 v30, v10, v30
	v_mul_f32_e32 v31, v11, v31
	v_mul_f32_e32 v24, v24, v54
	v_mul_f32_e32 v24, v0, v24
	v_mul_f32_e32 v25, v25, v54
	v_mul_f32_e32 v25, v1, v25
	s_waitcnt vmcnt(6)
	v_add_f32_e32 v63, 1.0, v68
	v_add_f32_e32 v68, 1.0, v69
	v_fma_f32 v28, v63, v28, v64
	v_add_f32_e32 v69, 1.0, v70
	v_add_f32_e32 v70, 1.0, v71
	v_fma_f32 v29, v68, v29, v65
	v_cvt_pk_bf16_f32 v28, v28, v29
	v_fma_f32 v30, v69, v30, v66
	v_fmac_f32_e32 v67, v70, v31
	v_cvt_pk_bf16_f32 v29, v30, v67
	global_store_dwordx2 v[50:51], v[28:29], off
	s_waitcnt vmcnt(5)
	v_add_f32_e32 v28, 1.0, v76
	v_fma_f32 v24, v28, v24, v72
	v_add_f32_e32 v28, 1.0, v77
	v_mul_f32_e32 v26, v26, v54
	v_fma_f32 v25, v28, v25, v73
	v_mul_f32_e32 v26, v2, v26
	v_add_f32_e32 v28, 1.0, v78
	v_mul_f32_e32 v27, v27, v54
	v_fma_f32 v26, v28, v26, v74
	v_mul_f32_e32 v27, v3, v27
	v_add_f32_e32 v28, 1.0, v79
	v_cvt_pk_bf16_f32 v24, v24, v25
	v_mul_f32_e32 v20, v20, v54
	v_fmac_f32_e32 v75, v28, v27
	v_cvt_pk_bf16_f32 v25, v26, v75
	global_store_dwordx2 v[50:51], v[24:25], off offset:512
	v_mul_f32_e32 v20, v4, v20
	s_waitcnt vmcnt(4)
	v_add_f32_e32 v24, 1.0, v80
	v_mul_f32_e32 v21, v21, v54
	v_fma_f32 v20, v24, v20, v84
	v_mul_f32_e32 v21, v5, v21
	v_add_f32_e32 v24, 1.0, v81
	v_mul_f32_e32 v22, v22, v54
	v_fma_f32 v21, v24, v21, v85
	v_mul_f32_e32 v22, v6, v22
	v_add_f32_e32 v24, 1.0, v82
	v_mul_f32_e32 v23, v23, v54
	v_fma_f32 v22, v24, v22, v86
	v_mul_f32_e32 v23, v7, v23
	v_add_f32_e32 v24, 1.0, v83
	v_cvt_pk_bf16_f32 v20, v20, v21
	v_mul_f32_e32 v16, v16, v54
	v_fmac_f32_e32 v87, v24, v23
	v_cvt_pk_bf16_f32 v21, v22, v87
	global_store_dwordx2 v[50:51], v[20:21], off offset:1024
	v_mul_f32_e32 v16, v12, v16
	s_waitcnt vmcnt(4)
	v_add_f32_e32 v20, 1.0, v88
	v_mul_f32_e32 v17, v17, v54
	s_waitcnt vmcnt(3)
	v_fma_f32 v16, v20, v16, v92
	v_mul_f32_e32 v17, v13, v17
	v_add_f32_e32 v20, 1.0, v89
	v_mul_f32_e32 v18, v18, v54
	v_fma_f32 v17, v20, v17, v93
	v_mul_f32_e32 v18, v14, v18
	v_add_f32_e32 v20, 1.0, v90
	v_mul_f32_e32 v19, v19, v54
	v_fma_f32 v18, v20, v18, v94
	v_mul_f32_e32 v19, v15, v19
	v_add_f32_e32 v20, 1.0, v91
	v_fmac_f32_e32 v95, v20, v19
	v_cvt_pk_bf16_f32 v16, v16, v17
	v_cvt_pk_bf16_f32 v17, v18, v95
	global_store_dwordx2 v[50:51], v[16:17], off offset:1536
	v_lshl_add_u64 v[50:51], v[50:51], 0, s[54:55]
	v_mov_b32_e32 v54, v62
	v_mov_b64_e32 v[28:29], v[32:33]
	v_mov_b64_e32 v[30:31], v[34:35]
	v_mov_b64_e32 v[24:25], v[36:37]
	v_mov_b64_e32 v[26:27], v[38:39]
	v_mov_b64_e32 v[20:21], v[40:41]
	v_mov_b64_e32 v[22:23], v[42:43]
	v_mov_b64_e32 v[16:17], v[44:45]
	v_mov_b64_e32 v[18:19], v[46:47]
	s_andn2_b64 exec, exec, s[8:9]
	s_cbranch_execz .LBB0_2950

.LBB0_3280:
	global_load_dwordx4 v[12:15], v[4:5], off offset:-2048
	global_load_dwordx4 v[16:19], v[4:5], off offset:-1024
	global_load_dwordx4 v[20:23], v[4:5], off
	global_load_dwordx4 v[24:27], v[4:5], off offset:1024
	global_load_dwordx4 v[28:31], v[2:3], off
	v_add_u32_e32 v0, s74, v0
	s_waitcnt vmcnt(4)
	v_mov_b32_e32 v34, v13
	s_waitcnt vmcnt(3)
	v_mov_b32_e32 v35, v17
	v_mov_b32_e32 v32, v12
	v_mov_b32_e32 v33, v16
	s_waitcnt vmcnt(2)
	v_mov_b32_e32 v42, v21
	s_waitcnt vmcnt(1)
	v_mov_b32_e32 v43, v25
	v_pk_mul_f32 v[34:35], v[34:35], v[34:35]
	v_mov_b32_e32 v36, v14
	v_mov_b32_e32 v37, v18
	v_mov_b32_e32 v40, v20
	v_mov_b32_e32 v41, v24
	v_pk_mul_f32 v[42:43], v[42:43], v[42:43]
	v_pk_fma_f32 v[32:33], v[32:33], v[32:33], v[34:35]
	v_mov_b32_e32 v38, v15
	v_mov_b32_e32 v39, v19
	v_mov_b32_e32 v44, v22
	v_mov_b32_e32 v45, v26
	v_pk_fma_f32 v[34:35], v[40:41], v[40:41], v[42:43]
	v_pk_fma_f32 v[32:33], v[36:37], v[36:37], v[32:33]
	v_mov_b32_e32 v46, v23
	v_mov_b32_e32 v47, v27
	v_pk_fma_f32 v[34:35], v[44:45], v[44:45], v[34:35]
	v_pk_fma_f32 v[32:33], v[38:39], v[38:39], v[32:33]
	v_pk_fma_f32 v[34:35], v[46:47], v[46:47], v[34:35]
	v_add_f32_e32 v32, v32, v33
	v_add_f32_e32 v32, v32, v34
	v_add_f32_e32 v32, v32, v35
	s_nop 1
	v_add_f32_dpp v32, v32, v32 quad_perm:[1,0,3,2] row_mask:0xf bank_mask:0xf bound_ctrl:1
	s_nop 1
	v_add_f32_dpp v32, v32, v32 quad_perm:[2,3,0,1] row_mask:0xf bank_mask:0xf bound_ctrl:1
	s_nop 1
	v_add_f32_dpp v32, v32, v32 row_ror:4 row_mask:0xf bank_mask:0xf bound_ctrl:1
	s_nop 1
	v_add_f32_dpp v32, v32, v32 row_ror:8 row_mask:0xf bank_mask:0xf bound_ctrl:1
	s_nop 1
	v_mov_b32_e32 v33, v32
	s_nop 1
	v_permlane16_swap_b32_e32 v33, v32
	v_add_f32_e32 v32, v32, v33
	v_mov_b32_e32 v33, v32
	s_nop 1
	v_permlane32_swap_b32_e32 v33, v32
	v_add_f32_e32 v32, v32, v33
	s_waitcnt lgkmcnt(0)
	v_fmamk_f32 v32, v32, 0x3a800000, v1
	v_mul_f32_e32 v33, 0x4b800000, v32
	v_cmp_gt_f32_e32 vcc, s4, v32
	s_nop 1
	v_cndmask_b32_e32 v32, v32, v33, vcc
	v_rsq_f32_e32 v32, v32
	s_nop 0
	v_mul_f32_e32 v33, 0x45800000, v32
	v_cndmask_b32_e32 v32, v32, v33, vcc
	v_pk_mul_f32 v[12:13], v[12:13], v[32:33] op_sel_hi:[1,0]
	v_pk_mul_f32 v[14:15], v[14:15], v[32:33] op_sel_hi:[1,0]
	s_waitcnt vmcnt(0)
	v_pk_mul_f32 v[12:13], v[28:29], v[12:13]
	v_pk_mul_f32 v[14:15], v[30:31], v[14:15]
	global_store_dwordx4 v[4:5], v[12:15], off offset:-2048
	global_load_dwordx4 v[12:15], v[2:3], off offset:1024
	v_pk_mul_f32 v[16:17], v[16:17], v[32:33] op_sel_hi:[1,0]
	v_pk_mul_f32 v[18:19], v[18:19], v[32:33] op_sel_hi:[1,0]
	v_cmp_lt_i32_e32 vcc, s5, v0
	s_or_b64 s[2:3], vcc, s[2:3]
	s_waitcnt vmcnt(0)
	v_pk_mul_f32 v[12:13], v[12:13], v[16:17]
	v_pk_mul_f32 v[14:15], v[14:15], v[18:19]
	global_store_dwordx4 v[4:5], v[12:15], off offset:-1024
	global_load_dwordx4 v[12:15], v[2:3], off offset:2048
	v_pk_mul_f32 v[16:17], v[20:21], v[32:33] op_sel_hi:[1,0]
	v_pk_mul_f32 v[18:19], v[22:23], v[32:33] op_sel_hi:[1,0]
	s_waitcnt vmcnt(0)
	v_pk_mul_f32 v[12:13], v[16:17], v[12:13]
	v_pk_mul_f32 v[14:15], v[18:19], v[14:15]
	global_store_dwordx4 v[4:5], v[12:15], off
	global_load_dwordx4 v[12:15], v[2:3], off offset:3072
	v_pk_mul_f32 v[16:17], v[24:25], v[32:33] op_sel_hi:[1,0]
	v_pk_mul_f32 v[18:19], v[26:27], v[32:33] op_sel_hi:[1,0]
	s_waitcnt vmcnt(0)
	v_pk_mul_f32 v[12:13], v[16:17], v[12:13]
	v_pk_mul_f32 v[14:15], v[18:19], v[14:15]
	global_store_dwordx4 v[4:5], v[12:15], off offset:1024
	v_lshl_add_u64 v[4:5], v[4:5], 0, s[0:1]
	s_andn2_b64 exec, exec, s[2:3]
	s_cbranch_execnz .LBB0_3280
